# grid barrier poll loops without s_sleep
# speedup vs baseline: 1.0041x; 1.0009x over previous
; __device__ __forceinline__ unsigned xb_ld(unsigned* p)              { return __hip_atomic_load(p, __ATOMIC_RELAXED, __HIP_MEMORY_SCOPE_AGENT); }
; __device__ __forceinline__ void xcd_barrier_complete(unsigned* bar, unsigned x, unsigned& nloc, unsigned& nx) {
;     const unsigned G = gridDim.x * gridDim.y * gridDim.z;
;     unsigned sum, cnt, mine, sp = 0u;
;     for (;;) {
;         sum = 0u; cnt = 0u; mine = 0u;
; #pragma unroll
;         for (unsigned j = 0; j < 16; ++j) { const unsigned c = xb_ld(&bar[XB_XCNT(j)]); sum += c; cnt += (c > 0u) ? 1u : 0u; mine = (j == x) ? c : mine; }
;         if (sum == G) break;
;         __builtin_amdgcn_s_sleep(1);
;         if ((++sp & 255u) == 0u) { if (xb_ld(&bar[XB_TMO])) break; if (sp > XB_SPIN_CAP) { atomicAdd(&bar[XB_TMO], 1u); break; } }
;     }
;     nloc = mine > 0u ? mine : 1u; nx = cnt > 0u ? cnt : 1u;
; }
.LBB0_2967:
	v_readlane_b32 s4, v253, 41
	v_readlane_b32 s5, v253, 42
	global_load_dword v10, v215, s[36:37] sc1
	s_waitcnt lgkmcnt(0)
	global_load_dword v0, v215, s[38:39] sc1
	global_load_dword v1, v215, s[40:41] sc1
	global_load_dword v2, v215, s[42:43] sc1
	global_load_dword v3, v215, s[44:45] sc1
	global_load_dword v4, v215, s[46:47] sc1
	global_load_dword v5, v215, s[48:49] sc1
	global_load_dword v6, v215, s[50:51] sc1
	global_load_dword v7, v215, s[52:53] sc1
	global_load_dword v8, v215, s[56:57] sc1
	global_load_dword v9, v215, s[68:69] sc1
	global_load_dword v11, v215, s[4:5] sc1
	v_readlane_b32 s4, v253, 43
	v_readlane_b32 s5, v253, 44
	v_readlane_b32 s6, v253, 57
	s_waitcnt vmcnt(10)
	v_add_u32_e32 v16, v0, v10
	s_nop 1
	global_load_dword v12, v215, s[4:5] sc1
	v_readlane_b32 s4, v253, 45
	v_readlane_b32 s5, v253, 46
	s_waitcnt vmcnt(10)
	v_add_u32_e32 v16, v16, v1
	s_waitcnt vmcnt(9)
	v_add_u32_e32 v16, v16, v2
	s_waitcnt vmcnt(8)
	v_add_u32_e32 v16, v16, v3
	s_waitcnt vmcnt(7)
	v_add_u32_e32 v16, v16, v4
	s_waitcnt vmcnt(6)
	v_add_u32_e32 v16, v16, v5
	global_load_dword v13, v215, s[4:5] sc1
	v_readlane_b32 s4, v253, 47
	v_readlane_b32 s5, v253, 48
	s_waitcnt vmcnt(6)
	v_add_u32_e32 v16, v16, v6
	s_waitcnt vmcnt(5)
	v_add_u32_e32 v16, v16, v7
	s_waitcnt vmcnt(4)
	v_add_u32_e32 v16, v16, v8
	s_waitcnt vmcnt(3)
	v_add_u32_e32 v16, v16, v9
	s_waitcnt vmcnt(2)
	v_add_u32_e32 v16, v16, v11
	global_load_dword v14, v215, s[4:5] sc1
	v_readlane_b32 s4, v253, 49
	v_readlane_b32 s5, v253, 50
	s_waitcnt vmcnt(2)
	v_add_u32_e32 v16, v16, v12
	s_nop 2
	global_load_dword v15, v215, s[4:5] sc1
	s_mov_b64 s[4:5], -1
	s_waitcnt vmcnt(2)
	v_add_u32_e32 v16, v16, v13
	s_waitcnt vmcnt(1)
	v_add_u32_e32 v16, v16, v14
	s_waitcnt vmcnt(0)
	v_add_u32_e32 v16, v16, v15
	v_cmp_eq_u32_e32 vcc, s6, v16
	s_mov_b64 s[6:7], -1
	s_cbranch_vccnz .LBB0_2966
	s_and_b32 s4, s11, 0xff
	s_cmp_eq_u32 s4, 0
	s_mov_b64 s[4:5], -1
	s_mov_b64 s[8:9], -1
	s_nop 0
	s_cbranch_scc0 .LBB0_2971
	global_load_dword v16, v215, s[34:35] sc1
	s_waitcnt vmcnt(0)
	v_cmp_eq_u32_e32 vcc, 0, v16
	s_cbranch_vccnz .LBB0_2973
	s_mov_b64 s[8:9], 0

; __device__ __forceinline__ unsigned xb_ld(unsigned* p)              { return __hip_atomic_load(p, __ATOMIC_RELAXED, __HIP_MEMORY_SCOPE_AGENT); }
; #define XB_SPIN(cond, bar) do { unsigned _sp = 0; while (cond) { __builtin_amdgcn_s_sleep(1); \
;     if ((++_sp & 255u) == 0u) { if (xb_ld(&(bar)[XB_TMO])) break; if (_sp > XB_SPIN_CAP) { atomicAdd(&(bar)[XB_TMO], 1u); break; } } } } while (0)
; __device__ __forceinline__ void xcd_barrier(const XcdBarrier& b) {
;     ...
;             else XB_SPIN(xb_ld(&bar[XB_TOPGEN]) == tg, bar);
.LBB0_2985:
	s_and_b32 s18, s22, 0xff
	s_mov_b64 s[16:17], -1
	s_cmp_lg_u32 s18, 0
	s_mov_b64 s[20:21], -1
	s_nop 0
	s_cbranch_scc1 .LBB0_2988
	global_load_dword v0, v215, s[34:35] sc1
	s_waitcnt vmcnt(0)
	v_cmp_eq_u32_e32 vcc, 0, v0
	s_cbranch_vccnz .LBB0_2990
	s_mov_b64 s[20:21], 0
	s_mov_b64 s[18:19], -1

; __device__ __forceinline__ unsigned xb_ld(unsigned* p)              { return __hip_atomic_load(p, __ATOMIC_RELAXED, __HIP_MEMORY_SCOPE_AGENT); }
; #define XB_SPIN(cond, bar) do { unsigned _sp = 0; while (cond) { __builtin_amdgcn_s_sleep(1); \
;     if ((++_sp & 255u) == 0u) { if (xb_ld(&(bar)[XB_TMO])) break; if (_sp > XB_SPIN_CAP) { atomicAdd(&(bar)[XB_TMO], 1u); break; } } } } while (0)
; __device__ __forceinline__ void xcd_barrier(const XcdBarrier& b) {
;     ...
;             XB_SPIN(xb_ld(&bar[XB_XGEN(b.x)]) == gen, bar);
.LBB0_3002:
	s_and_b32 s16, s20, 0xff
	s_mov_b64 s[14:15], -1
	s_cmp_lg_u32 s16, 0
	s_mov_b64 s[18:19], -1
	s_nop 0
	s_cbranch_scc1 .LBB0_3005
	global_load_dword v0, v215, s[34:35] sc1
	s_waitcnt vmcnt(0)
	v_cmp_eq_u32_e32 vcc, 0, v0
	s_cbranch_vccnz .LBB0_3007
	s_mov_b64 s[18:19], 0
	s_mov_b64 s[16:17], -1
